# attention half 2: ones-column MFMA issued early so the last six exps sit under the PV MFMA shadow instead of the MFMA-free loop tail
# baseline (speedup 1.0000x reference)
; #define LAS __attribute__((address_space(3)))
; template <bool FIRST>
; __device__ __forceinline__ void partialSM(f32x16& p0, f32x16& p1, f32x16& negm, float& dl, float& alpha) {
;     float pmax = p0[0];
; #pragma unroll
;     for (int r = 1; r < 16; ++r) pmax = fmaxf(pmax, p0[r]);
; #pragma unroll
;     for (int r = 0; r < 16; ++r) pmax = fmaxf(pmax, p1[r]);
;     { auto rr = __builtin_amdgcn_permlane32_swap(__float_as_uint(pmax), __float_as_uint(pmax), false, false);
;       pmax = fmaxf(__uint_as_float(rr[0]), __uint_as_float(rr[1])); }
;     if (FIRST) {
;         dl = 0.f; alpha = 1.f; const float d0_ = pmax - SH;
; #pragma unroll
;         for (int r = 0; r < 16; ++r) { p0[r] -= d0_; p1[r] -= d0_; negm[r] -= d0_; }
;     } else {
;         const bool keep = __all(pmax <= SH + THRL);
;         dl = keep ? 0.f : fmaxf(pmax - SH, 0.f); alpha = __builtin_amdgcn_exp2f(-dl);
;     }
; #pragma unroll
;     for (int r = 0; r < 16; ++r) p0[r] = __builtin_amdgcn_exp2f(p0[r]);
; }
; __device__ __forceinline__ void finishSM(f32x16& p0, f32x16& p1, v8i& pa) {
; #pragma unroll
;     for (int r = 0; r < 16; ++r) p1[r] = __builtin_amdgcn_exp2f(p1[r]);
; #pragma unroll
;     for (int w = 0; w < 4; ++w) { pa[w] = (int)pk4_fp8(p0[4 * w], p0[4 * w + 1], p0[4 * w + 2], p0[4 * w + 3]); pa[4 + w] = (int)pk4_fp8(p1[4 * w], p1[4 * w + 1], p1[4 * w + 2], p1[4 * w + 3]); }
; }
; __device__ __forceinline__ v8i ld32(const LAS char* a0, const LAS char* a1) { const v4i x = *(const LAS v4i*)a0, y = *(const LAS v4i*)a1; return (v8i){x[0], x[1], x[2], x[3], y[0], y[1], y[2], y[3]}; }
; __device__ __forceinline__ void qkt(f32x16& p0, f32x16& p1, const LAS char* Ks, int ka0, int ka1, const v8i* qf, const f32x16& negm) {
; #pragma unroll
;     for (int st = 0; st < 3; ++st) {
;         const v8i k0 = ld32(Ks + ka0 + 64 * st, Ks + ka1 + 64 * st), k1 = ld32(Ks + ka0 + 64 * st + 32 * 192, Ks + ka1 + 64 * st + 32 * 192);
;         if (st == 0) { p0 = MFMA8QK(k0, qf[st], negm); p1 = MFMA8QK(k1, qf[st], negm); }
;         else { p0 = MFMA8QK(k0, qf[st], p0); p1 = MFMA8QK(k1, qf[st], p1); } }
; }
; __device__ __forceinline__ void pv_d0(f32x16* o, const LAS char* Vs, int va0, int va1, v8i pa) {
; #pragma unroll
;     for (int d0 = 0; d0 < 4; ++d0) { const v8i vf = ld32(Vs + va0 + 2048 * d0, Vs + va1 + 2048 * d0); o[d0] = MFMA8(pa, vf, o[d0]); }
.LBB0_615:
	s_mul_hi_u32 s0, s15, 0xaaaaaaab
	s_lshr_b32 s0, s0, 1
	s_mul_i32 s0, s0, 0xffff4000
	s_bfe_i32 s1, s21, 0x10001
	s_and_b32 s1, s1, 0x6000
	s_add_i32 s1, s1, 0
	v_add_u32_e32 v0, s1, v244
	v_add_u32_e32 v161, s1, v245
	ds_read_b128 v[194:197], v0 offset:55360
	ds_read_b128 v[198:201], v161 offset:55360
	v_exp_f32_e32 v129, v129
	v_exp_f32_e32 v162, v133
	s_waitcnt lgkmcnt(4)
	v_mfma_scale_f32_32x32x64_f8f6f4 v[144:159], v[208:215], v[184:191], v[96:111], v234, v233 op_sel_hi:[0,0,0]
	ds_read_b128 v[202:205], v0 offset:49216
	ds_read_b128 v[206:209], v161 offset:49216
	v_exp_f32_e32 v130, v130
	v_exp_f32_e32 v131, v131
	v_exp_f32_e32 v134, v134
	v_exp_f32_e32 v135, v135
	s_waitcnt lgkmcnt(4)
	v_mfma_scale_f32_32x32x64_f8f6f4 v[112:127], v[120:127], v[184:191], v[96:111], v234, v233 op_sel_hi:[0,0,0]
	v_exp_f32_e32 v136, v136
	v_exp_f32_e32 v137, v137
	v_exp_f32_e32 v140, v140
	v_exp_f32_e32 v141, v141
	s_waitcnt lgkmcnt(2)
	v_mfma_scale_f32_32x32x64_f8f6f4 v[112:127], v[194:201], v[176:183], v[112:127], v234, v233 op_sel_hi:[0,0,0]
	v_exp_f32_e32 v138, v138
	v_exp_f32_e32 v139, v139
	v_exp_f32_e32 v142, v142
	v_exp_f32_e32 v143, v143
	s_waitcnt lgkmcnt(0)
	v_mfma_scale_f32_32x32x64_f8f6f4 v[144:159], v[202:209], v[176:183], v[144:159], v234, v233 op_sel_hi:[0,0,0]
	ds_read_b128 v[194:197], v0 offset:55424
	ds_read_b128 v[198:201], v161 offset:55424
	ds_read_b128 v[202:205], v0 offset:49280
	ds_read_b128 v[206:209], v161 offset:49280
	v_exp_f32_e32 v0, v128
	v_exp_f32_e32 v161, v132
	v_cvt_pk_fp8_f32 v132, v0, v129
	v_cvt_pk_fp8_f32 v133, v161, v162
	v_cvt_pk_fp8_f32 v128, v14, v15
	v_cvt_pk_fp8_f32 v132, v130, v131 op_sel:[0,0,1]
	v_cvt_pk_fp8_f32 v133, v134, v135 op_sel:[0,0,1]
	s_waitcnt lgkmcnt(0)
	v_mfma_scale_f32_32x32x64_f8f6f4 v[112:127], v[194:201], v[168:175], v[112:127], v234, v233 op_sel_hi:[0,0,0]
	v_cvt_pk_fp8_f32 v129, v10, v11
	v_cvt_pk_fp8_f32 v130, v6, v7
	v_cvt_pk_fp8_f32 v134, v136, v137
	v_cvt_pk_fp8_f32 v131, v2, v3
	v_cvt_pk_fp8_f32 v135, v140, v141
	v_cvt_pk_fp8_f32 v128, v192, v193 op_sel:[0,0,1]
	v_cvt_pk_fp8_f32 v129, v12, v13 op_sel:[0,0,1]
	v_cvt_pk_fp8_f32 v130, v8, v9 op_sel:[0,0,1]
	v_cvt_pk_fp8_f32 v134, v138, v139 op_sel:[0,0,1]
	v_cvt_pk_fp8_f32 v131, v4, v5 op_sel:[0,0,1]
	v_cvt_pk_fp8_f32 v135, v142, v143 op_sel:[0,0,1]
	v_or_b32_e32 v10, s0, v218
	v_or_b32_e32 v11, s0, v250
	v_add_u32_e32 v10, v247, v10
	v_add_u32_e32 v11, v247, v11
	ds_read_b128 v[2:5], v10
	ds_read_b128 v[6:9], v11
	v_mfma_scale_f32_32x32x64_f8f6f4 v[144:159], v[202:209], v[168:175], v[144:159], v234, v233 op_sel_hi:[0,0,0]
	ds_read_b128 v[194:197], v10 offset:2048
	ds_read_b128 v[198:201], v11 offset:2048
	v_mov_b32_e32 v161, v160
	v_mov_b32_e32 v162, v160
	v_mov_b32_e32 v163, v160
	v_mov_b32_e32 v164, v160
	v_mov_b32_e32 v165, v160
	v_mov_b32_e32 v166, v160
	v_mov_b32_e32 v167, v160
	s_waitcnt lgkmcnt(2)
	v_mfma_scale_f32_32x32x64_f8f6f4 v[64:79], v[128:135], v[2:9], v[64:79], v234, v234 op_sel_hi:[0,0,0]
	ds_read_b128 v[2:5], v10 offset:4096
	ds_read_b128 v[6:9], v11 offset:4096
	v_mfma_scale_f32_32x32x64_f8f6f4 v[80:95], v[128:135], v[160:167], v[80:95], v234, v234 op_sel_hi:[0,0,0]
	s_waitcnt lgkmcnt(2)
	v_mfma_scale_f32_32x32x64_f8f6f4 v[48:63], v[128:135], v[194:201], v[48:63], v234, v234 op_sel_hi:[0,0,0]
	ds_read_b128 v[194:197], v10 offset:6144
	ds_read_b128 v[198:201], v11 offset:6144
	s_nop 1
	v_exp_f32_e32 v228, v144
	v_exp_f32_e32 v229, v145
	v_exp_f32_e32 v220, v146
	v_exp_f32_e32 v221, v147
	v_exp_f32_e32 v226, v148
	s_waitcnt lgkmcnt(2)
	v_mfma_scale_f32_32x32x64_f8f6f4 v[32:47], v[128:135], v[2:9], v[32:47], v234, v234 op_sel_hi:[0,0,0]
	v_exp_f32_e32 v227, v149
	v_exp_f32_e32 v224, v150
	v_exp_f32_e32 v225, v151
	v_exp_f32_e32 v222, v152
	v_exp_f32_e32 v223, v153
	v_max_f32_e32 v0, v144, v145
	v_max3_f32 v0, v0, v146, v147
	v_max3_f32 v0, v0, v148, v149
	v_max3_f32 v0, v0, v150, v151
	v_max3_f32 v0, v0, v152, v153
	s_waitcnt lgkmcnt(0)
	v_mfma_scale_f32_32x32x64_f8f6f4 v[16:31], v[128:135], v[194:201], v[16:31], v234, v234 op_sel_hi:[0,0,0]
	s_bitcmp0_b32 s15, 0
	s_cselect_b32 s1, 0x6000, 0
	v_add_u32_e32 v12, s1, v244
	v_add_u32_e32 v13, s1, v245
	v_add_u32_e32 v14, 0xf000, v12
	v_add_u32_e32 v15, 0xf000, v13
	ds_read_b128 v[202:205], v12 offset:61440
	ds_read_b128 v[206:209], v13 offset:61440
	ds_read_b128 v[194:197], v14 offset:6144
	ds_read_b128 v[198:201], v15 offset:6144
	v_max3_f32 v0, v0, v154, v155
	v_max3_f32 v0, v0, v156, v157
	v_max3_f32 v0, v0, v158, v159
	v_exp_f32_e32 v162, v154
	v_exp_f32_e32 v163, v155
	v_max3_f32 v0, v0, v112, v113
	v_max3_f32 v0, v0, v114, v115
	v_exp_f32_e32 v166, v156
	v_exp_f32_e32 v167, v157
	v_max3_f32 v0, v0, v116, v117
	v_max3_f32 v0, v0, v118, v119
	v_exp_f32_e32 v164, v158
	v_exp_f32_e32 v165, v159
	v_max3_f32 v0, v0, v120, v121
	v_max3_f32 v0, v0, v122, v123
	v_max3_f32 v0, v0, v124, v125
	v_max3_f32 v0, v0, v126, v127
	v_mov_b32_e32 v2, v0
	s_nop 1
	v_permlane32_swap_b32_e32 v0, v2
	v_max_f32_e32 v0, v0, v2
	v_cmp_ge_f32_e32 vcc, s67, v0
	s_nop 0
	s_cmp_lg_u64 vcc, exec
	s_cbranch_scc0 .LBB0_588
	v_add_f32_e32 v2, -4.0, v0
	v_max_f32_e32 v2, 0, v2
	v_exp_f32_e64 v0, -v2
	s_and_saveexec_b64 s[0:1], s[12:13]
	s_cbranch_execz .LBB0_587
	ds_write_b32 v243, v0 offset:128
	s_branch .LBB0_587
